# in-proj GEMM: context-row tiles that produce no output (outside the kv_a columns) are not computed
# baseline (speedup 1.0000x reference)
.LBB0_164:
	s_cmp_lt_u32 s88, 64
	s_cbranch_scc1 .Lp2_keep
	s_sub_u32 s101, s86, 13
	s_cmp_lt_u32 s101, 2
	s_cbranch_scc1 .Lp2_keep
	s_mov_b64 s[0:1], 0
